# context NA pairs dispatched to waves with lw%32==16 instead of 0, so they no longer land on the workgroups that also run the context attention units (on top of v11)
# baseline (speedup 1.0000x reference)
.LBB0_182:
	s_or_b64 exec, exec, s[0:1]
	s_and_b32 s0, s80, -8
	s_add_i32 s5, s20, s0
	s_min_i32 s6, s5, 0xff
	s_and_b32 s0, s6, 1
	s_bfe_u32 s4, s80, 0x10002
	s_ashr_i32 s2, s5, 1
	s_lshl_b32 s17, s0, 5
	s_cmp_eq_u32 s0, 0
	s_cselect_b64 s[0:1], -1, 0
	v_writelane_b32 v251, s0, 23
	v_mbcnt_hi_u32_b32 v202, -1, v135
	v_writelane_b32 v254, s86, 0
	v_writelane_b32 v251, s1, 24
	s_and_b64 s[0:1], s[0:1], exec
	s_cselect_b32 s11, 16, 48
	s_ashr_i32 s12, s5, 5
	s_lshl_b32 s3, s4, 13
	s_lshl_b32 s0, s2, 6
	s_add_i32 s13, s12, 0x100
	s_add_i32 s0, s0, s3
	s_lshl_b32 s8, s4, 8
	s_min_i32 s15, s13, 0xff
	s_or_b32 s7, s0, s17
	s_lshl_b32 s1, s5, 5
	s_or_b32 s9, s8, 0x2000
	v_writelane_b32 v251, s11, 25
	s_or_b32 s11, s11, s0
	s_and_b32 s0, s15, 1
	s_add_i32 s10, s9, s1
	s_ashr_i32 s14, s13, 1
	s_lshl_b32 s18, s0, 5
	s_cmp_eq_u32 s0, 0
	s_cselect_b64 s[0:1], -1, 0
	v_writelane_b32 v251, s0, 26
	v_writelane_b32 v254, s87, 1
	v_writelane_b32 v254, s88, 2
	v_writelane_b32 v251, s1, 27
	s_and_b64 s[0:1], s[0:1], exec
	s_cselect_b32 s16, 16, 48
	s_lshl_b32 s0, s14, 6
	s_add_i32 s0, s0, s3
	s_lshl_b32 s13, s13, 5
	s_or_b32 s1, s0, s18
	s_add_i32 s9, s9, s13
	v_writelane_b32 v251, s16, 28
	s_or_b32 s13, s16, s0
	s_or_b32 s16, s10, 16
	s_cmpk_gt_i32 s5, 0xff
	s_cselect_b32 s0, s10, s7
	s_cselect_b32 s19, 4, 12
	s_or_b32 s7, s9, 16
	s_cmp_gt_i32 s12, -1
	v_writelane_b32 v251, s0, 29
	s_cselect_b32 s1, s9, s1
	s_cselect_b32 s0, 0, s14
	v_writelane_b32 v251, s1, 30
	s_cselect_b32 s12, 4, 12
	s_cselect_b32 s1, s7, s13
	s_cmpk_gt_i32 s5, 0xff
	v_writelane_b32 v251, s1, 31
	s_cselect_b32 s1, 0, s2
	s_cselect_b32 s2, s16, s11
	v_writelane_b32 v251, s2, 32
	s_lshl_b32 s2, s80, 3
	s_add_i32 s14, s20, s2
	s_lshl_b32 s20, s94, 3
	s_add_i32 s13, s21, s33
	s_add_u32 s22, s92, 0xa200000
	s_addc_u32 s23, s93, 0
	s_add_u32 s26, s92, 0xc300000
	s_addc_u32 s27, s93, 0
	s_add_u32 s10, s92, 0x11dc0000
	s_addc_u32 s11, s93, 0
	v_writelane_b32 v249, s10, 58
	v_writelane_b32 v254, s89, 3
	v_writelane_b32 v254, s30, 4
	v_writelane_b32 v249, s11, 59
	s_add_u32 s10, s92, 0x12e40000
	s_addc_u32 s11, s93, 0
	s_add_u32 s28, s92, 0x13260000
	s_addc_u32 s29, s93, 0
	s_add_u32 s36, s92, 0x13680000
	s_addc_u32 s37, s93, 0
	s_add_u32 s38, s92, 0x13ec0000
	s_addc_u32 s39, s93, 0
	s_add_u32 s40, s92, 0x14700000
	s_addc_u32 s41, s93, 0
	s_add_u32 s42, s92, 0x14f40000
	s_addc_u32 s43, s93, 0
	v_writelane_b32 v249, s42, 56
	v_writelane_b32 v254, s31, 5
	v_writelane_b32 v254, s34, 6
	v_writelane_b32 v249, s43, 57
	s_add_u32 s42, s92, 0x15f40000
	s_addc_u32 s43, s93, 0
	v_writelane_b32 v251, s42, 33
	v_writelane_b32 v254, s35, 7
	s_movk_i32 s60, 0xc000
	v_writelane_b32 v251, s43, 34
	s_add_u32 s42, s92, 0x15fc0000
	s_addc_u32 s43, s93, 0
	v_writelane_b32 v251, s42, 35
	v_writelane_b32 v254, s90, 8
	v_mov_b32_e32 v199, 0x358637bd
	v_writelane_b32 v251, s43, 36
	s_add_u32 s42, s92, 0x17040000
	s_addc_u32 s43, s93, 0
	s_add_u32 s2, s92, 0x19140000
	v_writelane_b32 v251, s2, 37
	s_addc_u32 s2, s93, 0
	s_add_u32 s44, s92, 0x1d340000
	v_writelane_b32 v251, s2, 38
	s_addc_u32 s45, s93, 0
	v_writelane_b32 v251, s44, 39
	s_cmpk_lt_i32 s14, 0x4200
	v_mov_b32_e32 v200, 0x260
	v_writelane_b32 v251, s45, 40
	s_cselect_b64 s[44:45], -1, 0
	v_writelane_b32 v251, s44, 41
	s_cmpk_lt_i32 s80, 0x252
	v_mov_b32_e32 v201, 1
	v_writelane_b32 v251, s45, 42
	s_cselect_b64 s[44:45], -1, 0
	s_lshr_b32 s2, s81, 29
	s_add_i32 s2, s80, s2
	s_ashr_i32 s16, s2, 3
	s_and_b32 s2, s2, -8
	s_sub_i32 s21, s80, s2
	s_mul_i32 s2, s21, 0x4a
	s_add_i32 s7, s2, 2
	s_ashr_i32 s2, s94, 31
	v_writelane_b32 v251, s44, 43
	s_cmpk_lt_i32 s80, 0x100
	v_writelane_b32 v250, s2, 11
	v_writelane_b32 v251, s45, 44
	s_cselect_b64 s[44:45], -1, 0
	v_writelane_b32 v251, s44, 45
	s_cmp_lt_i32 s80, 32
	v_xor_b32_e32 v204, 1, v202
	v_writelane_b32 v251, s45, 46
	s_cselect_b64 s[44:45], -1, 0
	v_writelane_b32 v251, s44, 47
	s_ashr_i32 s2, s80, 2
	s_and_b32 s9, s80, 1
	v_writelane_b32 v251, s45, 48
	v_writelane_b32 v251, s2, 49
	s_and_b32 s2, s2, 30
	s_or_b32 s2, s2, s9
	s_cmpk_lg_i32 s94, 0x100
	s_cselect_b64 s[44:45], -1, 0
	v_writelane_b32 v251, s44, 50
	s_cmpk_lt_i32 s80, 0x200
	v_xor_b32_e32 v205, 2, v202
	v_writelane_b32 v251, s45, 51
	s_cselect_b64 s[44:45], -1, 0
	v_writelane_b32 v251, s44, 52
	s_lshl_b32 s2, s2, 8
	s_or_b32 s2, s3, s2
	v_writelane_b32 v251, s45, 53
	v_writelane_b32 v251, s2, 54
	s_and_b32 s2, s33, 4
	v_writelane_b32 v251, s2, 55
	s_mul_i32 s2, s4, 0x210000
	s_add_u32 s3, s10, s2
	v_writelane_b32 v251, s3, 56
	v_writelane_b32 v251, s10, 57
	s_addc_u32 s3, s11, 0
	s_mul_i32 s4, s4, 0x420000
	v_writelane_b32 v251, s11, 58
	v_writelane_b32 v251, s3, 59
	s_add_u32 s3, s28, s2
	v_writelane_b32 v251, s3, 60
	v_writelane_b32 v251, s28, 61
	s_addc_u32 s3, s29, 0
	s_cmp_lt_i32 s80, 16
	v_writelane_b32 v251, s29, 62
	v_writelane_b32 v251, s3, 63
	s_cselect_b64 s[10:11], -1, 0
	s_max_i32 s3, s1, 4
	v_writelane_b32 v252, s10, 0
	s_add_i32 s9, s3, -4
	s_and_b32 s3, s80, 3
	v_writelane_b32 v252, s11, 1
	s_lshl_b32 s10, s3, 6
	s_lshl_b32 s11, s3, 7
	s_add_u32 s28, s36, s11
	v_writelane_b32 v252, s36, 2
	s_addc_u32 s29, s37, 0
	s_or_b32 s8, s8, s10
	v_writelane_b32 v252, s37, 3
	v_writelane_b32 v252, s28, 4
	s_mulk_i32 s8, 0x4200
	s_mul_i32 s1, s1, 31
	v_writelane_b32 v252, s29, 5
	s_add_u32 s28, s40, s8
	v_writelane_b32 v252, s40, 6
	s_addc_u32 s29, s41, 0
	v_xor_b32_e32 v206, 4, v202
	v_writelane_b32 v252, s41, 7
	v_writelane_b32 v252, s28, 8
	v_xor_b32_e32 v208, 16, v202
	v_xor_b32_e32 v209, 32, v202
	v_writelane_b32 v252, s29, 9
	s_min_u32 s28, s9, 0x78
	s_add_u32 s4, s38, s4
	v_writelane_b32 v252, s38, 10
	s_addc_u32 s8, s39, 0
	s_add_u32 s36, s4, s11
	v_writelane_b32 v252, s39, 11
	s_addc_u32 s37, s8, 0
	v_writelane_b32 v252, s36, 12
	s_bitcmp1_b32 s6, 0
	s_cselect_b64 s[8:9], -1, 0
	v_writelane_b32 v252, s37, 13
	s_and_b32 s4, s5, 31
	v_writelane_b32 v252, s8, 14
	s_cmp_eq_u32 s4, 16
	s_cselect_b64 s[4:5], -1, 0
	v_writelane_b32 v252, s9, 15
	v_writelane_b32 v252, s4, 16
	v_mov_b32_e32 v248, 0xffffff00
	v_mov_b32_e32 v207, 0x8100
	v_writelane_b32 v252, s5, 17
	s_max_i32 s4, s0, 4
	s_add_i32 s4, s4, -4
	s_min_u32 s29, s4, 0x78
	s_bitcmp1_b32 s15, 0
	s_cselect_b64 s[4:5], -1, 0
	v_writelane_b32 v252, s4, 18
	s_cmpk_lt_i32 s13, 0x200
	s_mul_i32 s0, s0, 31
	v_writelane_b32 v252, s5, 19
	v_writelane_b32 v252, s13, 20
	s_cselect_b64 s[4:5], -1, 0
	v_writelane_b32 v252, s4, 21
	s_add_i32 s8, s80, 64
	v_mov_b32_e32 v212, 0x1200
	v_writelane_b32 v252, s5, 22
	s_lshl_b32 s4, s21, 5
	s_cmp_lt_i32 s21, 2
	s_mul_i32 s5, s21, 0x4b
	s_cselect_b32 s5, s5, s7
	s_add_i32 s5, s5, s16
	s_mul_hi_i32 s6, s5, 0x38e38e39
	s_lshr_b32 s7, s6, 31
	s_ashr_i32 s6, s6, 4
	s_add_i32 s6, s6, s7
	s_mul_i32 s7, s6, 0x48
	s_lshl_b32 s6, s6, 3
	s_sub_i32 s7, s5, s7
	s_sub_i32 s5, 0x42, s6
	s_min_u32 s9, s5, 8
	v_writelane_b32 v252, s19, 23
	s_add_i32 s5, s19, -1
	v_writelane_b32 v252, s5, 24
	v_writelane_b32 v252, s12, 25
	s_add_i32 s5, s12, -1
	v_writelane_b32 v252, s5, 26
	s_cmp_lt_i32 s21, 0
	s_mul_i32 s5, s21, 33
	s_cselect_b32 s4, s5, s4
	s_add_i32 s4, s4, s16
	s_ashr_i32 s5, s4, 31
	s_lshr_b32 s5, s5, 27
	s_add_i32 s5, s4, s5
	s_and_b32 s10, s5, 0xffe0
	s_sub_i32 s4, s4, s10
	s_bfe_i32 s10, s4, 0x80000
	s_bfe_u32 s10, s10, 0x3000c
	s_add_i32 s10, s4, s10
	s_and_b32 s12, s10, 0xf8
	s_sub_i32 s4, s4, s12
	s_ashr_i32 s5, s5, 5
	s_bfe_i32 s10, s10, 0x80000
	v_writelane_b32 v252, s21, 27
	s_lshl_b32 s5, s5, 3
	s_sext_i32_i16 s10, s10
	s_sext_i32_i8 s4, s4
	v_writelane_b32 v252, s16, 28
	s_add_i32 s12, s5, s4
	s_ashr_i32 s4, s10, 3
	v_writelane_b32 v252, s4, 29
	s_lshr_b32 s4, s10, 3
	s_bfe_i64 s[4:5], s[4:5], 0x100000
	s_lshl_b64 s[4:5], s[4:5], 19
	s_ashr_i32 s13, s12, 31
	v_writelane_b32 v252, s4, 30
	v_cvt_f32_ubyte0_e32 v1, s9
	s_mov_b32 s10, s12
	v_writelane_b32 v252, s5, 31
	s_lshl_b64 s[4:5], s[12:13], 19
	s_add_u32 s4, s42, s4
	s_addc_u32 s5, s43, s5
	s_add_u32 s36, s4, 0x40000
	v_writelane_b32 v252, s4, 32
	s_addc_u32 s37, s5, 0
	s_waitcnt lgkmcnt(0)
	v_cvt_f32_i32_e32 v0, s7
	v_writelane_b32 v252, s5, 33
	v_writelane_b32 v252, s36, 34
	s_mul_i32 s5, s12, 0x160000
	v_rcp_iflag_f32_e32 v2, v1
	v_writelane_b32 v252, s37, 35
	s_mul_hi_i32 s4, s12, 0x160000
	v_writelane_b32 v252, s10, 36
	s_add_u32 s12, s26, s5
	s_addc_u32 s13, s27, s4
	v_writelane_b32 v252, s11, 37
	s_add_u32 s4, s12, 0xb0000
	v_writelane_b32 v252, s12, 38
	s_addc_u32 s5, s13, 0
	v_mul_f32_e32 v2, v0, v2
	v_writelane_b32 v252, s13, 39
	v_writelane_b32 v252, s4, 40
	v_trunc_f32_e32 v2, v2
	v_fma_f32 v0, -v2, v1, v0
	v_writelane_b32 v252, s5, 41
	s_ashr_i32 s4, s7, 30
	s_or_b32 s10, s4, 1
	v_cmp_ge_f32_e64 s[4:5], |v0|, v1
	v_cvt_i32_f32_e32 v0, v2
	s_and_b64 s[4:5], s[4:5], exec
	s_cselect_b32 s4, s10, 0
	v_mov_b32_e32 v1, 0
	v_readfirstlane_b32 s5, v0
	s_add_i32 s4, s5, s4
	s_mul_i32 s5, s4, s9
	s_sub_i32 s5, s7, s5
	s_sext_i32_i8 s5, s5
	s_add_i32 s12, s6, s5
	s_bfe_i64 s[6:7], s[4:5], 0x80000
	s_lshl_b64 s[6:7], s[6:7], 19
	v_writelane_b32 v252, s6, 42
	s_ashr_i32 s13, s12, 31
	s_sext_i32_i8 s4, s4
	v_writelane_b32 v252, s7, 43
	s_mov_b32 s6, s12
	v_writelane_b32 v252, s6, 44
	v_mov_b32_e32 v236, v1
	v_mov_b32_e32 v237, v1
	v_writelane_b32 v252, s7, 45
	s_lshl_b64 s[6:7], s[12:13], 19
	s_add_u32 s6, s22, s6
	v_writelane_b32 v249, s22, 50
	s_addc_u32 s7, s23, s7
	v_writelane_b32 v252, s4, 46
	s_add_u32 s4, s6, 0x40000
	v_writelane_b32 v252, s6, 47
	s_addc_u32 s5, s7, 0
	v_writelane_b32 v249, s23, 51
	v_writelane_b32 v252, s7, 48
	v_writelane_b32 v252, s4, 49
	v_mov_b32_e32 v238, v1
	v_mov_b32_e32 v239, v1
	v_writelane_b32 v252, s5, 50
	s_add_u32 s4, s42, s11
	s_addc_u32 s5, s43, 0
	v_writelane_b32 v252, s4, 51
	v_mov_b32_e32 v213, 0x4200
	s_movk_i32 s95, 0x4200
	v_writelane_b32 v252, s5, 52
	s_abs_i32 s4, s94
	v_cvt_f32_u32_e32 v0, s4
	s_sub_i32 s5, 0, s4
	s_movk_i32 s33, 0x3fff
	s_mov_b32 s63, 0x41000000
	v_rcp_iflag_f32_e32 v0, v0
	s_mov_b64 s[54:55], 0x80
	s_mov_b64 s[58:59], 0x8000
	s_mov_b32 s61, -1
	v_mul_f32_e32 v0, 0x4f7ffffe, v0
	v_cvt_u32_f32_e32 v0, v0
	v_writelane_b32 v254, s91, 9
	s_barrier
	v_readfirstlane_b32 s6, v0
	s_mul_i32 s5, s5, s6
	s_mul_hi_u32 s5, s6, s5
	s_add_i32 s6, s6, s5
	s_abs_i32 s5, s8
	s_mul_hi_u32 s6, s5, s6
	s_mul_i32 s6, s6, s4
	s_sub_i32 s5, s5, s6
	s_ashr_i32 s6, s8, 31
	s_sub_i32 s7, s5, s4
	s_cmp_ge_u32 s5, s4
	s_cselect_b32 s5, s7, s5
	s_sub_i32 s7, s5, s4
	s_cmp_ge_u32 s5, s4
	s_cselect_b32 s4, s7, s5
	s_xor_b32 s4, s4, s6
	s_sub_i32 s8, s4, s6
	s_cmp_lt_i32 s8, 32
	s_cselect_b64 s[4:5], -1, 0
	v_writelane_b32 v252, s4, 53
	v_and_b32_e32 v0, 64, v202
	v_add_u32_e32 v203, 64, v0
	v_writelane_b32 v252, s5, 54
	s_ashr_i32 s4, s8, 31
	s_lshr_b32 s5, s4, 30
	s_add_i32 s5, s8, s5
	s_ashr_i32 s6, s5, 2
	s_lshr_b32 s4, s4, 28
	s_lshr_b32 s7, s6, 30
	s_add_i32 s4, s8, s4
	s_add_i32 s7, s6, s7
	s_ashr_i32 s4, s4, 4
	s_and_b32 s7, s7, -4
	s_sub_i32 s10, s6, s7
	s_add_i32 s6, s4, 64
	s_and_b32 s5, s5, -4
	s_mov_b32 s4, s6
	s_ashr_i32 s7, s6, 31
	s_sub_i32 s12, s8, s5
	v_writelane_b32 v252, s4, 55
	s_ashr_i32 s13, s12, 31
	s_ashr_i32 s11, s10, 31
	v_writelane_b32 v252, s5, 56
	s_lshl_b64 s[4:5], s[6:7], 19
	s_mov_b32 s6, s12
	v_writelane_b32 v252, s6, 57
	s_lshl_b64 s[12:13], s[12:13], 9
	s_nop 0
	v_writelane_b32 v252, s7, 58
	s_mov_b32 s6, s10
	v_writelane_b32 v252, s6, 59
	s_nop 1
	v_writelane_b32 v252, s7, 60
	s_lshl_b64 s[6:7], s[10:11], 19
	s_add_u32 s4, s42, s4
	v_writelane_b32 v252, s6, 61
	v_writelane_b32 v250, s42, 15
	s_addc_u32 s5, s43, s5
	v_writelane_b32 v252, s7, 62
	s_add_u32 s4, s4, s12
	v_writelane_b32 v252, s12, 63
	s_addc_u32 s5, s5, s13
	s_add_u32 s6, s4, 0x40000
	v_writelane_b32 v253, s13, 0
	v_writelane_b32 v253, s4, 1
	s_addc_u32 s7, s5, 0
	s_cmpk_lt_i32 s8, 0x58
	v_writelane_b32 v253, s5, 2
	v_writelane_b32 v253, s6, 3
	s_mul_hi_i32 s4, s8, 0x2e8ba2e9
	v_writelane_b32 v250, s43, 16
	v_writelane_b32 v253, s7, 4
	s_cselect_b64 s[6:7], -1, 0
	v_writelane_b32 v253, s6, 5
	s_ashr_i32 s5, s4, 1
	s_nop 0
	v_writelane_b32 v253, s7, 6
	s_lshr_b32 s6, s4, 31
	s_add_i32 s5, s5, s6
	s_ashr_i32 s4, s4, 3
	s_add_i32 s4, s4, s6
	s_ashr_i32 s6, s5, 31
	s_lshr_b32 s6, s6, 30
	s_add_i32 s6, s5, s6
	s_and_b32 s6, s6, -4
	s_sub_i32 s6, s5, s6
	s_mul_i32 s5, s5, 11
	v_writelane_b32 v253, s8, 7
	s_sub_i32 s8, s8, s5
	v_writelane_b32 v253, s6, 8
	s_mul_i32 s5, s6, 0x160000
	s_add_i32 s7, s4, 64
	s_ashr_i32 s9, s8, 31
	v_writelane_b32 v253, s5, 9
	s_ashr_i32 s5, s5, 31
	s_mul_i32 s4, s7, 0x160000
	v_writelane_b32 v253, s5, 10
	s_mov_b32 s6, s8
	s_lshl_b64 s[8:9], s[8:9], 9
	v_writelane_b32 v253, s6, 11
	s_add_u32 s4, s26, s4
	s_mul_hi_i32 s5, s7, 0x160000
	v_writelane_b32 v253, s7, 12
	v_writelane_b32 v250, s26, 13
	s_addc_u32 s5, s27, s5
	v_writelane_b32 v253, s7, 13
	s_add_u32 s4, s4, s8
	v_writelane_b32 v253, s8, 14
	s_addc_u32 s5, s5, s9
	s_add_u32 s6, s4, 0xb0000
	v_writelane_b32 v253, s9, 15
	v_writelane_b32 v253, s4, 16
	s_addc_u32 s7, s5, 0
	s_ashr_i32 s15, s14, 31
	v_writelane_b32 v253, s5, 17
	s_lshl_b64 s[4:5], s[14:15], 11
	s_add_u32 s4, s92, s4
	s_addc_u32 s5, s93, s5
	v_writelane_b32 v253, s6, 18
	s_add_u32 s4, s4, 0xa200000
	s_addc_u32 s5, s5, 0
	v_writelane_b32 v253, s7, 19
	v_writelane_b32 v253, s4, 20
	s_ashr_i32 s21, s20, 31
	v_writelane_b32 v249, s20, 52
	v_writelane_b32 v253, s5, 21
	s_lshl_b64 s[4:5], s[20:21], 11
	v_writelane_b32 v253, s4, 22
	v_writelane_b32 v250, s27, 14
	v_writelane_b32 v249, s21, 53
	v_writelane_b32 v253, s5, 23
	s_add_u32 s4, s92, 0x13edfe00
	v_writelane_b32 v253, s4, 24
	s_addc_u32 s4, s93, 0
	v_writelane_b32 v253, s4, 25
	s_lshl_b32 s4, s80, 6
	v_writelane_b32 v253, s4, 26
	s_lshl_b32 s4, s94, 6
	v_writelane_b32 v253, s4, 27
	s_add_u32 s4, s92, 0x1303c000
	v_writelane_b32 v253, s4, 28
	s_addc_u32 s4, s93, 0
	s_add_u32 s2, s92, s2
	v_writelane_b32 v253, s4, 29
	s_addc_u32 s4, s93, 0
	s_add_u32 s2, s2, 0x1303c000
	v_writelane_b32 v253, s2, 30
	s_addc_u32 s2, s4, 0
	v_writelane_b32 v253, s2, 31
	s_mul_i32 s2, s3, 0x1d1
	s_mul_i32 s3, s28, 31
	v_writelane_b32 v253, s28, 32
	s_add_i32 s3, s2, s3
	s_sub_i32 s1, s3, s1
	v_writelane_b32 v253, s29, 33
	s_mul_i32 s3, s29, 31
	s_addk_i32 s1, 0x6c
	v_writelane_b32 v253, s17, 34
	s_add_i32 s2, s2, s3
	v_writelane_b32 v253, s1, 35
	s_sub_i32 s1, s1, s17
	s_sub_i32 s0, s2, s0
	v_writelane_b32 v253, s1, 36
	s_addk_i32 s0, 0x6c
	v_writelane_b32 v253, s18, 37
	v_writelane_b32 v253, s0, 38
	s_sub_i32 s0, s0, s18
	v_writelane_b32 v253, s0, 39
	v_writelane_b32 v253, s14, 40
	s_add_i32 s0, s14, 0xffffc000
	s_mov_b32 s1, 2
	v_writelane_b32 v253, s15, 41
	v_writelane_b32 v253, s0, 42
	s_add_i32 s0, 0, 0x20000
	v_writelane_b32 v253, s0, 43
	s_add_i32 s0, 0, 0x20004
	v_writelane_b32 v253, s0, 44
	s_add_i32 s0, 0, 0x1e800
	v_writelane_b32 v253, s0, 45
	s_add_i32 s0, 0, 0x10080
	v_writelane_b32 v253, s0, 46
	v_writelane_b32 v253, s0, 47
	s_mov_b32 s15, 0
	s_mov_b32 s21, 0xf800000
	v_writelane_b32 v253, s1, 48
	s_mov_b64 s[0:1], 0
	v_writelane_b32 v253, s0, 49
	s_mov_b32 s20, 0x3e38aa3b
	s_mov_b32 s6, s15
	v_writelane_b32 v253, s1, 50
	s_mov_b64 s[0:1], s[68:69]
	v_writelane_b32 v253, s0, 51
	s_nop 1
	v_writelane_b32 v253, s1, 52
	v_writelane_b32 v253, s62, 53
	v_writelane_b32 v253, s70, 54
	s_nop 1
	v_writelane_b32 v253, s71, 55
	v_writelane_b32 v253, s72, 56
	s_nop 1
	v_writelane_b32 v253, s73, 57
	v_writelane_b32 v253, s74, 58
	s_nop 1
	v_writelane_b32 v253, s75, 59
	v_writelane_b32 v253, s76, 60
	s_nop 1
	v_writelane_b32 v253, s77, 61
	v_writelane_b32 v253, s84, 62
	s_nop 1
	v_writelane_b32 v253, s85, 63
	s_branch .LBB0_184
